# v95: v93 + differential-head bias/mask tiles through the hand-scheduled tile body, bias and -inf mask as QK accumulator init from a per-unit LDS table
# speedup vs baseline: 1.0080x; 1.0080x over previous
; #define LAS __attribute__((address_space(3)))
; #define ATT_WAITV(n) asm volatile("s_waitcnt vmcnt(" #n ")" ::: "memory")
; template <int MODE>
; __device__ __forceinline__ void attn_unit(const Params& P, LAS unsigned char* lds, const int b, const int h, const int qb) {
;     ...
;         if (tid < 129) ((LAS float*)(lds + AL_BIAS))[tid] = tab[h * 132 + tid] - tab[h * 132 + 128];
;     }
;     const int krow = 4 * w + (lane >> 4), kchunk = (lane & 15) ^ (krow & 15);
;     const bf16_t* kg = Kb_ + (size_t)krow * RS + kchunk * 8;
;     const int vst = 2 * w + (lane >> 5), vkey = (vst >> 2) * 8 + ((lane >> 2) & 7);
;     const bf16_t* vg = Vb_ + (size_t)vkey * RS + (vst & 3) * 32 + (lane & 3) * 8;
;     const float* cg_ = Cl + lane;
;     ...
;     const int pr = (r & 19) | ((r & 4) << 1) | ((r & 8) >> 1);
;     const unsigned kra = pr * 256, kswz = pr & 15;
;     const unsigned vra = 16384 + hh * 2048 + ((lane & 15) >> 2) * 64 + ((lane >> 4) & 1) * 32 + (lane & 3) * 8;
;     f32x16 O[4];
; #pragma unroll
;     for (int d = 0; d < 4; ++d)
; #pragma unroll
;         for (int i = 0; i < 16; ++i) O[d][i] = 0.f;
;     float m1 = ONLINE ? -INFINITY : 0.f, l1 = 0.f;
;     const int ktw_last = (q0w + 31) / 64;
;     ATT_WAITV(0); __builtin_amdgcn_s_barrier(); asm volatile("" ::: "memory");
; #pragma unroll
;     for (int i = 0; i < AL_PD; ++i) if (kt0 + i < nt) ATT_DMA(kt0 + i, i);
.LBB0_470:
	s_or_b64 exec, exec, s[66:67]
	s_mul_i32 s22, s96, 0x84
	s_mov_b32 s23, s13
	s_lshl_b64 s[22:23], s[22:23], 2
	s_add_u32 s22, s56, s22
	s_addc_u32 s23, s57, s23
	v_lshrrev_b32_e32 v240, 8, v6
	v_and_b32_e32 v241, 0xff, v6
	v_add_u32_e32 v240, v240, v241
	v_sub_u32_e32 v240, 0xbf, v240
	v_med3_i32 v241, v240, 0, v235
	v_lshlrev_b32_e32 v241, 2, v241
	global_load_dword v242, v241, s[22:23]
	v_add_u32_e32 v243, -2, v240
	v_med3_i32 v244, v243, 0, v235
	v_lshlrev_b32_e32 v244, 2, v244
	global_load_dword v245, v244, s[22:23]
	global_load_dword v246, v1, s[22:23] offset:512
	v_lshlrev_b32_e32 v247, 2, v6
	v_add_u32_e32 v247, 0x22a00, v247
	s_waitcnt vmcnt(0)
	v_sub_f32_e32 v242, v242, v246
	v_sub_f32_e32 v245, v245, v246
	v_cmp_gt_i32_e32 vcc, 0, v240
	v_cndmask_b32_e32 v242, v242, v231, vcc
	v_cmp_gt_i32_e32 vcc, 0, v243
	v_cndmask_b32_e32 v245, v245, v231, vcc
	ds_write_b32 v247, v242
	ds_write_b32 v247, v245 offset:2048
	s_waitcnt lgkmcnt(0)
	s_lshl_b64 s[66:67], s[8:9], 1
	s_add_u32 s40, s88, s66
	s_addc_u32 s41, s89, s67
	v_and_b32_e32 v151, 63, v6
	s_add_u32 s68, s90, s66
	s_addc_u32 s69, s91, s67
	s_lshl_b32 s39, s11, 2
	v_lshrrev_b32_e32 v10, 4, v151
	v_or_b32_e32 v2, s39, v10
	s_ashr_i32 s22, s58, 4
	v_lshrrev_b32_e32 v0, 2, v6
	v_bitop3_b32 v9, s39, v6, v10 bitop3:0x36
	v_ashrrev_i32_e32 v3, 31, v2
	s_lshl_b32 s23, s11, 1
	v_bfi_b32 v4, -8, s22, v0
	v_lshlrev_b32_e32 v0, 3, v6
	v_lshlrev_b64 v[2:3], 8, v[2:3]
	v_ashrrev_i32_e32 v5, 31, v4
	v_and_or_b32 v11, s23, 2, v7
	v_and_b32_e32 v156, 24, v0
	v_lshlrev_b32_e32 v0, 4, v9
	s_lshl_b32 s23, s11, 10
	v_lshlrev_b64 v[12:13], 8, v[4:5]
	v_lshl_add_u64 v[2:3], s[40:41], 0, v[2:3]
	v_and_b32_e32 v0, 0xf0, v0
	s_add_i32 s77, s23, 0x100
	v_lshl_add_u64 v[4:5], v[2:3], 0, v[0:1]
	v_lshl_add_u64 v[2:3], s[68:69], 0, v[12:13]
	v_lshlrev_b32_e32 v0, 6, v11
	s_waitcnt vmcnt(0)
	s_barrier
	s_mov_b32 m0, s77
	v_lshl_add_u64 v[2:3], v[2:3], 0, v[0:1]
	v_lshlrev_b32_e32 v0, 1, v156
	global_load_lds_dwordx4 v[4:5], off
	v_lshl_add_u64 v[12:13], v[4:5], 0, s[28:29]
	s_add_i32 m0, s77, 0x2000
	v_lshl_add_u64 v[2:3], v[2:3], 0, v[0:1]
	global_load_lds_dwordx4 v[12:13], off
	s_add_i32 m0, s77, 0x4000
	v_lshl_add_u64 v[12:13], v[2:3], 0, s[28:29]
	global_load_lds_dwordx4 v[2:3], off
	s_add_i32 m0, s77, 0x6000
	s_nop 0
	global_load_lds_dwordx4 v[12:13], off
	s_add_i32 m0, s77, 0x8000
	v_lshl_add_u64 v[12:13], v[4:5], 0, s[30:31]
	global_load_lds_dwordx4 v[12:13], off
	v_lshl_add_u64 v[12:13], v[4:5], 0, s[36:37]
	s_add_i32 m0, s77, 0xa000
	s_nop 0
	global_load_lds_dwordx4 v[12:13], off
	v_lshl_add_u64 v[12:13], v[2:3], 0, s[30:31]
	s_add_i32 m0, s77, 0xc000
	s_nop 0
	global_load_lds_dwordx4 v[12:13], off
	v_lshl_add_u64 v[12:13], v[2:3], 0, s[36:37]
	s_add_i32 m0, s77, 0xe000
	s_cmp_eq_u32 s10, 63
	global_load_lds_dwordx4 v[12:13], off
	s_cbranch_scc1 .LBB0_472
	s_mov_b64 s[40:41], 0x8000
	s_add_i32 m0, s77, 0x10000
	v_lshl_add_u64 v[12:13], v[4:5], 0, s[40:41]
	s_mov_b64 s[68:69], 0xa000
	global_load_lds_dwordx4 v[12:13], off
	v_lshl_add_u64 v[4:5], v[4:5], 0, s[68:69]
	s_add_i32 m0, s77, 0x12000
	s_nop 0
	global_load_lds_dwordx4 v[4:5], off
	v_lshl_add_u64 v[4:5], v[2:3], 0, s[40:41]
	s_add_i32 m0, s77, 0x14000
	v_lshl_add_u64 v[2:3], v[2:3], 0, s[68:69]
	global_load_lds_dwordx4 v[4:5], off
	s_add_i32 m0, s77, 0x16000
	s_nop 0
	global_load_lds_dwordx4 v[2:3], off
.LBB0_472:
	v_and_b32_e32 v2, 19, v6
	v_lshlrev_b32_e32 v3, 1, v6
	v_and_or_b32 v2, v3, 8, v2
	v_lshrrev_b32_e32 v3, 1, v6
	v_and_b32_e32 v3, 4, v3
	v_or_b32_e32 v4, v2, v3
	v_bitop3_b32 v2, v2, 15, v3 bitop3:0xc8
	v_lshlrev_b32_e32 v3, 4, v6
	v_and_b32_e32 v160, 0xc0, v3
	v_lshl_or_b32 v3, s1, 3, v7
	v_lshlrev_b32_e32 v159, 8, v4
	v_bitop3_b32 v4, v4, v3, 15 bitop3:0x6c
	v_lshlrev_b32_e32 v161, 4, v4
	v_bitop3_b32 v4, v3, v2, 2 bitop3:0x36
	v_lshlrev_b32_e32 v164, 4, v4
	v_bitop3_b32 v4, v3, v2, 4 bitop3:0x36
	v_bitop3_b32 v2, v3, v2, 6 bitop3:0x36
	s_add_i32 s38, s99, s38
	v_lshlrev_b32_e32 v148, 3, v7
	v_lshlrev_b32_e32 v166, 4, v2
	v_add_u32_e32 v2, s38, v8
	v_sub_u32_e32 v167, v2, v148
	v_add_u32_e32 v2, s39, v10
	v_ashrrev_i32_e32 v3, 31, v2
	v_lshlrev_b32_e32 v165, 4, v4
	v_lshlrev_b64 v[2:3], 8, v[2:3]
	v_and_b32_e32 v4, 15, v9
	s_and_b32 s70, s22, -8
	v_bfe_u32 v0, v6, 2, 3
	s_add_i32 s38, s97, s33
	v_lshl_or_b32 v2, v4, 4, v2
	s_add_i32 s40, s38, s98
	v_lshl_add_u64 v[152:153], s[52:53], 0, v[2:3]
	v_add_u32_e32 v2, s70, v0
	s_lshl_b32 s38, s58, 1
	v_ashrrev_i32_e32 v3, 31, v2
	v_and_b32_e32 v0, 3, v6
	s_and_b32 s38, s38, 0x80
	v_lshlrev_b64 v[2:3], 8, v[2:3]
	v_lshlrev_b32_e32 v0, 4, v0
	v_lshl_or_b32 v4, v7, 6, s38
	v_lshlrev_b32_e32 v5, 5, v10
	v_or3_b32 v2, v2, v0, v4
	v_mov_b32_e32 v14, v1
	v_mov_b32_e32 v15, v1
	v_lshlrev_b32_e32 v157, 11, v7
	v_and_b32_e32 v158, 32, v5
	s_add_i32 s22, s99, 0x80
	s_mov_b32 s41, s13
	v_lshl_add_u64 v[154:155], s[52:53], 0, v[2:3]
	v_mov_b32_e32 v0, v1
	v_mov_b32_e32 v2, v1
	v_mov_b32_e32 v3, v1
	v_mov_b32_e32 v4, v1
	v_mov_b32_e32 v5, v1
	v_mov_b32_e32 v6, v1
	v_mov_b32_e32 v7, v1
	v_mov_b32_e32 v8, v1
	v_mov_b32_e32 v9, v1
	v_mov_b32_e32 v10, v1
	v_mov_b32_e32 v11, v1
	v_mov_b32_e32 v12, v1
	v_mov_b32_e32 v13, v1
	v_mov_b64_e32 v[30:31], v[14:15]
	v_mov_b64_e32 v[46:47], v[14:15]
	v_mov_b64_e32 v[62:63], v[14:15]
	v_mov_b64_e32 v[78:79], v[14:15]
	v_lshlrev_b32_e32 v149, 7, v162
	s_lshr_b32 s22, s22, 6
	s_lshr_b32 s23, s59, 6
	s_add_i32 s75, s59, 0xffffff41
	s_lshl_b64 s[68:69], s[40:41], 21
	s_mov_b32 s38, 0
	v_mov_b32_e32 v163, 0
	s_mov_b32 s39, 63
	v_mov_b64_e32 v[28:29], v[12:13]
	v_mov_b64_e32 v[26:27], v[10:11]
	v_mov_b64_e32 v[24:25], v[8:9]
	v_mov_b64_e32 v[22:23], v[6:7]
	v_mov_b64_e32 v[20:21], v[4:5]
	v_mov_b64_e32 v[18:19], v[2:3]
	v_mov_b64_e32 v[16:17], v[0:1]
	v_mov_b64_e32 v[44:45], v[12:13]
	v_mov_b64_e32 v[42:43], v[10:11]
	v_mov_b64_e32 v[40:41], v[8:9]
	v_mov_b64_e32 v[38:39], v[6:7]
	v_mov_b64_e32 v[36:37], v[4:5]
	v_mov_b64_e32 v[34:35], v[2:3]
	v_mov_b64_e32 v[32:33], v[0:1]
	v_mov_b64_e32 v[60:61], v[12:13]
	v_mov_b64_e32 v[58:59], v[10:11]
	v_mov_b64_e32 v[56:57], v[8:9]
	v_mov_b64_e32 v[54:55], v[6:7]
	v_mov_b64_e32 v[52:53], v[4:5]
	v_mov_b64_e32 v[50:51], v[2:3]
	v_mov_b64_e32 v[48:49], v[0:1]
	v_mov_b64_e32 v[76:77], v[12:13]
	v_mov_b64_e32 v[74:75], v[10:11]
	v_mov_b64_e32 v[72:73], v[8:9]
	v_mov_b64_e32 v[70:71], v[6:7]
	v_mov_b64_e32 v[68:69], v[4:5]
	v_mov_b64_e32 v[66:67], v[2:3]
	v_mov_b64_e32 v[64:65], v[0:1]
	v_sub_u32_e32 v201, 3, v162
	v_and_b32_e32 v201, 3, v201
	v_mul_u32_u24_e32 v201, 0x3fc, v201
	v_lshlrev_b32_e32 v200, 2, v162
	v_sub_u32_e32 v200, v201, v200
	v_and_b32_e32 v201, 32, v178
	v_add_u32_e32 v200, v200, v201
	v_add_u32_e32 v200, 0x22cfc, v200
	s_mov_b32 s40, 0
	s_waitcnt vmcnt(0)
	s_branch .LBB0_475

; template <int MODE>
; __device__ __forceinline__ void attn_unit(const Params& P, LAS unsigned char* lds, const int b, const int h, const int qb) {
;     ...
;             if constexpr (MODE == 1) {
;                 bf16x8 kf[8];
;                 const unsigned kb_ = (unsigned)(uintptr_t)Kb + kra, c0 = mp * 8 + hh;
;                 k_issue4(kf, kb_ + (((c0) ^ kswz) << 4), kb_ + (((c0 + 2) ^ kswz) << 4), kb_ + (((c0 + 4) ^ kswz) << 4), kb_ + (((c0 + 6) ^ kswz) << 4));
;                 v_issue<0>(va, vaddr);
;                 k_wait<8>(kf);
; #pragma unroll
;                 for (int ks = 0; ks < 4; ++ks) { s[0] = MFMA32(kf[2 * ks], Qf[ks], s[0]); s[1] = MFMA32(kf[2 * ks + 1], Qf[ks], s[1]); }
;                 v_issue<1>(vb, vaddr);
;             } else {
; #pragma unroll
;             for (int ks = 0; ks < NQ; ++ks) {
;                 const unsigned chunk = mp * 8 + 2 * ks + hh;
;                 const unsigned off = kra + ((chunk ^ kswz) << 4);
;                 const bf16x8 a0 = *(const LAS bf16x8*)(Kb + off), a1 = *(const LAS bf16x8*)(Kb + off + 8192);
;                 s[0] = MFMA32(a0, Qf[ks], s[0]); s[1] = MFMA32(a1, Qf[ks], s[1]);
;             }
;             v_issue<0>(va, vaddr);
;             }
;             if (FOX) {
;                 const LAS float* cl = (const LAS float*)(lds + AL_CLS + (cur * 8 + w) * 256) + 8 * hh;
; #pragma unroll
;                 for (int blk = 0; blk < 2; ++blk)
; #pragma unroll
;                     for (int j4 = 0; j4 < 4; ++j4) { const f32x4 c = *(const LAS f32x4*)(cl + 32 * blk + 16 * (j4 >> 1) + 4 * (j4 & 1));
; #pragma unroll
;                         for (int e = 0; e < 4; ++e) s[blk][4 * j4 + e] -= c[e]; }
;             } else if (q0w - kt * 64 - 63 < 128) {
;                 const LAS float* bl = (const LAS float*)(lds + AL_BIAS);
; #pragma unroll
;                 for (int blk = 0; blk < 2; ++blk)
; #pragma unroll
;                     for (int i = 0; i < 16; ++i) { const int dist = q - (kbase + 32 * blk + 16 * (i >> 3) + (i & 7)); const int di = dist < 0 ? 0 : (dist > 128 ? 128 : dist); s[blk][i] += bl[di]; }
;             }
;             if (kt * 64 + 63 > q0w) {
; #pragma unroll
;                 for (int blk = 0; blk < 2; ++blk)
; #pragma unroll
;                     for (int i = 0; i < 16; ++i) { if (kbase + 32 * blk + 16 * (i >> 3) + (i & 7) > q) s[blk][i] = -INFINITY; }
;             }
.Lm1_slow2:
	s_lshl_b32 s41, s39, 2
	s_sub_i32 s41, s41, 0xfc
	v_add_u32_e32 v201, s41, v200
	ds_read_b128 v[96:99], v201
	ds_read_b128 v[100:103], v201 offset:16
	ds_read_b128 v[104:107], v201 offset:64
	ds_read_b128 v[108:111], v201 offset:80
	ds_read_b128 v[80:83], v201 offset:128
	ds_read_b128 v[84:87], v201 offset:144
	ds_read_b128 v[88:91], v201 offset:192
	ds_read_b128 v[92:95], v201 offset:208
	s_waitcnt lgkmcnt(4)
	v_mfma_f32_32x32x16_bf16 v[96:111], v[2:5], v[112:115], v[96:111]
	v_mfma_f32_32x32x16_bf16 v[96:111], v[10:13], v[116:119], v[96:111]
	v_mfma_f32_32x32x16_bf16 v[96:111], v[168:171], v[120:123], v[96:111]
	v_mfma_f32_32x32x16_bf16 v[96:111], v[180:183], v[124:127], v[96:111]
	s_waitcnt lgkmcnt(0)
	ds_read_b64_tr_b16 v[168:169], v0 offset:0x1000
	ds_read_b64_tr_b16 v[170:171], v0 offset:0x1100
	ds_read_b64_tr_b16 v[10:11], v0 offset:0x1200
	ds_read_b64_tr_b16 v[12:13], v0 offset:0x1300
	ds_read_b64_tr_b16 v[180:181], v0 offset:0x1400
	ds_read_b64_tr_b16 v[182:183], v0 offset:0x1500
	ds_read_b64_tr_b16 v[2:3], v0 offset:0x1600
	ds_read_b64_tr_b16 v[4:5], v0 offset:0x1700
	v_mfma_f32_32x32x16_bf16 v[80:95], v[6:9], v[112:115], v[80:95]
	s_nop 2
	v_exp_f32_e32 v14, v96
	v_exp_f32_e32 v15, v97
	v_mfma_f32_32x32x16_bf16 v[80:95], v[128:131], v[116:119], v[80:95]
	v_exp_f32_e32 v240, v98
	v_exp_f32_e32 v241, v99
	v_exp_f32_e32 v242, v100
	v_mfma_f32_32x32x16_bf16 v[80:95], v[172:175], v[120:123], v[80:95]
	v_exp_f32_e32 v243, v101
	v_exp_f32_e32 v244, v102
	v_exp_f32_e32 v245, v103
	v_mfma_f32_32x32x16_bf16 v[80:95], v[184:187], v[124:127], v[80:95]
	v_cvt_pk_bf16_f32 v96, v14, v15
	v_cvt_pk_bf16_f32 v97, v240, v241
	v_cvt_pk_bf16_f32 v98, v242, v243
	v_cvt_pk_bf16_f32 v99, v244, v245
	v_exp_f32_e32 v246, v104
	s_waitcnt lgkmcnt(8)
	v_mfma_f32_32x32x16_bf16 v[64:79], v[144:147], v[96:99], v[64:79]
	ds_read_b64_tr_b16 v[6:7], v0 offset:0x2000
	ds_read_b64_tr_b16 v[8:9], v0 offset:0x2100
	ds_read_b64_tr_b16 v[128:129], v0 offset:0x2200
	ds_read_b64_tr_b16 v[130:131], v0 offset:0x2300
	ds_read_b64_tr_b16 v[172:173], v0 offset:0x2400
	ds_read_b64_tr_b16 v[174:175], v0 offset:0x2500
	ds_read_b64_tr_b16 v[184:185], v0 offset:0x2600
	ds_read_b64_tr_b16 v[186:187], v0 offset:0x2700
	v_mfma_f32_32x32x16_bf16 v[48:63], v[140:143], v[96:99], v[48:63]
	v_exp_f32_e32 v247, v105
	v_exp_f32_e32 v248, v106
	v_exp_f32_e32 v249, v107
	v_mfma_f32_32x32x16_bf16 v[32:47], v[136:139], v[96:99], v[32:47]
	v_exp_f32_e32 v250, v108
	v_exp_f32_e32 v251, v109
	v_exp_f32_e32 v252, v110
	v_mfma_f32_32x32x16_bf16 v[16:31], v[132:135], v[96:99], v[16:31]
	v_exp_f32_e32 v253, v111
	v_add_f32_e32 v14, v15, v14
	v_cvt_pk_bf16_f32 v100, v246, v247
	v_cvt_pk_bf16_f32 v101, v248, v249
	v_cvt_pk_bf16_f32 v102, v250, v251
	v_add_f32_e32 v14, v240, v14
	v_cvt_pk_bf16_f32 v103, v252, v253
	v_add_f32_e32 v14, v241, v14
	s_waitcnt lgkmcnt(8)
	v_mfma_f32_32x32x16_bf16 v[64:79], v[168:171], v[100:103], v[64:79]
	ds_read_b64_tr_b16 v[144:145], v0 offset:0x3000
	ds_read_b64_tr_b16 v[146:147], v0 offset:0x3100
	ds_read_b64_tr_b16 v[140:141], v0 offset:0x3200
	ds_read_b64_tr_b16 v[142:143], v0 offset:0x3300
	ds_read_b64_tr_b16 v[136:137], v0 offset:0x3400
	ds_read_b64_tr_b16 v[138:139], v0 offset:0x3500
	ds_read_b64_tr_b16 v[132:133], v0 offset:0x3600
	ds_read_b64_tr_b16 v[134:135], v0 offset:0x3700
	v_mfma_f32_32x32x16_bf16 v[48:63], v[10:13], v[100:103], v[48:63]
	v_exp_f32_e32 v104, v80
	v_exp_f32_e32 v105, v81
	v_exp_f32_e32 v106, v82
	v_mfma_f32_32x32x16_bf16 v[32:47], v[180:183], v[100:103], v[32:47]
	v_exp_f32_e32 v107, v83
	v_exp_f32_e32 v108, v84
	v_exp_f32_e32 v109, v85
	v_mfma_f32_32x32x16_bf16 v[16:31], v[2:5], v[100:103], v[16:31]
	v_exp_f32_e32 v110, v86
	v_exp_f32_e32 v111, v87
	v_cvt_pk_bf16_f32 v80, v104, v105
	v_cvt_pk_bf16_f32 v81, v106, v107
	v_cvt_pk_bf16_f32 v82, v108, v109
	v_add_f32_e32 v14, v242, v14
	v_cvt_pk_bf16_f32 v83, v110, v111
	v_add_f32_e32 v14, v243, v14
	s_waitcnt lgkmcnt(8)
	v_mfma_f32_32x32x16_bf16 v[64:79], v[6:9], v[80:83], v[64:79]
	v_exp_f32_e32 v2, v88
	v_exp_f32_e32 v3, v89
	v_exp_f32_e32 v4, v90
	v_mfma_f32_32x32x16_bf16 v[48:63], v[128:131], v[80:83], v[48:63]
	v_exp_f32_e32 v5, v91
	v_exp_f32_e32 v10, v92
	v_exp_f32_e32 v11, v93
	v_mfma_f32_32x32x16_bf16 v[32:47], v[172:175], v[80:83], v[32:47]
	v_exp_f32_e32 v12, v94
	v_exp_f32_e32 v13, v95
	v_add_f32_e32 v14, v244, v14
	v_add_f32_e32 v14, v245, v14
	v_mfma_f32_32x32x16_bf16 v[16:31], v[184:187], v[80:83], v[16:31]
	v_cvt_pk_bf16_f32 v84, v2, v3
	v_cvt_pk_bf16_f32 v85, v4, v5
	v_cvt_pk_bf16_f32 v86, v10, v11
	v_add_f32_e32 v14, v246, v14
	v_cvt_pk_bf16_f32 v87, v12, v13
	v_add_f32_e32 v14, v247, v14
	v_add_f32_e32 v14, v248, v14
	s_waitcnt lgkmcnt(0)
	v_add_f32_e32 v14, v249, v14
	v_add_f32_e32 v14, v250, v14
	v_add_f32_e32 v14, v251, v14
	v_add_f32_e32 v14, v252, v14
	v_add_f32_e32 v14, v253, v14
	s_add_i32 s41, s40, 3
	s_cmp_ge_u32 s41, s22
	s_cbranch_scc1 .Lm1s_nodma
	s_cmpk_gt_u32 s58, 0xff
	s_cbranch_scc1 .Lm1s_nodma
	v_mfma_f32_32x32x16_bf16 v[64:79], v[144:147], v[84:87], v[64:79]
	s_mov_b64 s[70:71], 0x1000
	s_add_i32 s41, s38, 0x18000
	s_and_b32 s41, s41, 0x18000
	s_add_i32 s41, s77, s41
	v_lshl_add_u64 v[240:241], v[152:153], 0, s[68:69]
	v_lshl_add_u64 v[242:243], v[240:241], 0, s[42:43]
	s_mov_b32 m0, s41
	v_lshl_add_u64 v[240:241], v[240:241], 0, s[44:45]
	global_load_lds_dwordx4 v[242:243], off
	v_mfma_f32_32x32x16_bf16 v[48:63], v[140:143], v[84:87], v[48:63]
	s_add_i32 m0, s41, 0x1000
	v_lshl_add_u64 v[242:243], v[242:243], 0, s[70:71]
	global_load_lds_dwordx4 v[242:243], off
	s_add_i32 m0, s41, 0x2000
	v_lshl_add_u64 v[242:243], v[240:241], 0, s[70:71]
	global_load_lds_dwordx4 v[240:241], off
	s_add_i32 m0, s41, 0x3000
	v_lshl_add_u64 v[240:241], v[154:155], 0, s[68:69]
	global_load_lds_dwordx4 v[242:243], off
	v_add_f32_e32 v14, v104, v14
	v_add_f32_e32 v14, v105, v14
	v_add_f32_e32 v14, v106, v14
	v_add_f32_e32 v14, v107, v14
	v_mfma_f32_32x32x16_bf16 v[32:47], v[136:139], v[84:87], v[32:47]
	v_lshl_add_u64 v[242:243], v[240:241], 0, s[48:49]
	s_add_i32 m0, s41, 0x4000
	v_lshl_add_u64 v[240:241], v[240:241], 0, s[50:51]
	global_load_lds_dwordx4 v[242:243], off
	s_add_i32 m0, s41, 0x5000
	v_lshl_add_u64 v[242:243], v[242:243], 0, s[70:71]
	global_load_lds_dwordx4 v[242:243], off
	v_add_f32_e32 v14, v108, v14
	v_add_f32_e32 v14, v109, v14
	v_add_f32_e32 v14, v110, v14
	v_add_f32_e32 v14, v111, v14
	v_add_f32_e32 v14, v2, v14
	v_add_f32_e32 v14, v3, v14
	v_mfma_f32_32x32x16_bf16 v[16:31], v[132:135], v[84:87], v[16:31]
	s_add_i32 m0, s41, 0x6000
	v_lshl_add_u64 v[242:243], v[240:241], 0, s[70:71]
	global_load_lds_dwordx4 v[240:241], off
	s_add_i32 m0, s41, 0x7000
	s_nop 0
	global_load_lds_dwordx4 v[242:243], off
	v_add_f32_e32 v14, v4, v14
	v_add_f32_e32 v14, v5, v14
	v_add_f32_e32 v14, v10, v14
	v_add_f32_e32 v14, v11, v14
	v_add_f32_e32 v14, v12, v14
	v_add_f32_e32 v14, v13, v14
	v_add_f32_e32 v163, v163, v14
	s_branch .LBB0_474
; #define MFMA32(a, b, c) __builtin_amdgcn_mfma_f32_32x32x16_bf16((a), (b), (c), 0, 0, 0)
; #define ATT_PV(v_, p_) do { const bf16x8 pf_ = __builtin_bit_cast(bf16x8, (p_)); _Pragma("unroll") for (int d = 0; d < 4; ++d) { \
;         const bf16x8 vf_ = __builtin_shufflevector((v_)[2 * d], (v_)[2 * d + 1], 0, 1, 2, 3, 4, 5, 6, 7); O[d] = MFMA32(vf_, pf_, O[d]); } } while (0)
; template <int MODE>
; __device__ __forceinline__ void attn_unit(const Params& P, LAS unsigned char* lds, const int b, const int h, const int qb) {
;     ...
;             if constexpr (MODE == 1) {
;                 bf16x8 kf[8];
;                 const unsigned kb_ = (unsigned)(uintptr_t)Kb + kra, c0 = mp * 8 + hh;
;                 k_issue4(kf, kb_ + (((c0) ^ kswz) << 4), kb_ + (((c0 + 2) ^ kswz) << 4), kb_ + (((c0 + 4) ^ kswz) << 4), kb_ + (((c0 + 6) ^ kswz) << 4));
;                 v_issue<0>(va, vaddr);
;                 k_wait<8>(kf);
; #pragma unroll
;                 for (int ks = 0; ks < 4; ++ks) { s[0] = MFMA32(kf[2 * ks], Qf[ks], s[0]); s[1] = MFMA32(kf[2 * ks + 1], Qf[ks], s[1]); }
;                 v_issue<1>(vb, vaddr);
;     ...
;                 v_issue<2>(vc, vaddr); v_wait<15>(va); ATT_PV(va, pk1[0]); v_issue<3>(vd, vaddr); v_wait<15>(vb); ATT_PV(vb, pk1[1]); v_wait<8>(vc); ATT_PV(vc, pk1[2]); v_wait<0>(vd); ATT_PV(vd, pk1[3]);
.Lm1s_nodma:
	v_mfma_f32_32x32x16_bf16 v[64:79], v[144:147], v[84:87], v[64:79]
	v_add_f32_e32 v14, v104, v14
	v_add_f32_e32 v14, v105, v14
	v_add_f32_e32 v14, v106, v14
	v_add_f32_e32 v14, v107, v14
	v_add_f32_e32 v14, v108, v14
	v_add_f32_e32 v14, v109, v14
	v_mfma_f32_32x32x16_bf16 v[48:63], v[140:143], v[84:87], v[48:63]
	v_add_f32_e32 v14, v110, v14
	v_add_f32_e32 v14, v111, v14
	v_add_f32_e32 v14, v2, v14
	v_add_f32_e32 v14, v3, v14
	v_add_f32_e32 v14, v4, v14
	v_add_f32_e32 v14, v5, v14
	v_mfma_f32_32x32x16_bf16 v[32:47], v[136:139], v[84:87], v[32:47]
	v_add_f32_e32 v14, v10, v14
	v_add_f32_e32 v14, v11, v14
	v_add_f32_e32 v14, v12, v14
	v_add_f32_e32 v14, v13, v14
	v_add_f32_e32 v163, v163, v14
	v_mfma_f32_32x32x16_bf16 v[16:31], v[132:135], v[84:87], v[16:31]
	s_branch .LBB0_474
	s_sub_i32 s41, s39, 63
	v_mfma_f32_32x32x16_bf16 v[96:111], v[2:5], v[112:115], 0
	s_cmp_le_i32 s41, s75
	v_mfma_f32_32x32x16_bf16 v[80:95], v[6:9], v[112:115], 0
	v_mfma_f32_32x32x16_bf16 v[96:111], v[10:13], v[116:119], v[96:111]
	v_mfma_f32_32x32x16_bf16 v[80:95], v[128:131], v[116:119], v[80:95]
	ds_read_b64_tr_b16 v[128:129], v0 offset:0x1000
	ds_read_b64_tr_b16 v[130:131], v0 offset:0x1100
	ds_read_b64_tr_b16 v[10:11], v0 offset:0x1200
	ds_read_b64_tr_b16 v[12:13], v0 offset:0x1300
	ds_read_b64_tr_b16 v[6:7], v0 offset:0x1400
	ds_read_b64_tr_b16 v[8:9], v0 offset:0x1500
	ds_read_b64_tr_b16 v[2:3], v0 offset:0x1600
	ds_read_b64_tr_b16 v[4:5], v0 offset:0x1700
	v_mfma_f32_32x32x16_bf16 v[96:111], v[168:171], v[120:123], v[96:111]
	v_mfma_f32_32x32x16_bf16 v[80:95], v[172:175], v[120:123], v[80:95]
	v_mfma_f32_32x32x16_bf16 v[96:111], v[180:183], v[124:127], v[96:111]
	v_mfma_f32_32x32x16_bf16 v[80:95], v[184:187], v[124:127], v[80:95]
	s_cbranch_scc1 .LBB0_488
; #define LAS __attribute__((address_space(3)))
; template <int MODE>
; __device__ __forceinline__ void attn_unit(const Params& P, LAS unsigned char* lds, const int b, const int h, const int qb) {
;     ...
;             } else if (q0w - kt * 64 - 63 < 128) {
;                 const LAS float* bl = (const LAS float*)(lds + AL_BIAS);
; #pragma unroll
;                 for (int blk = 0; blk < 2; ++blk)
; #pragma unroll
;                     for (int i = 0; i < 16; ++i) { const int dist = q - (kbase + 32 * blk + 16 * (i >> 3) + (i & 7)); const int di = dist < 0 ? 0 : (dist > 128 ? 128 : dist); s[blk][i] += bl[di]; }
;             }
	v_max_i32_e32 v15, 1, v167
	v_max_i32_e32 v168, 2, v167
	v_max_i32_e32 v169, 3, v167
	v_max_i32_e32 v170, 4, v167
	v_max_i32_e32 v171, 5, v167
	v_max_i32_e32 v172, 6, v167
	v_max_i32_e32 v173, 7, v167
	v_max_i32_e32 v174, 16, v167
	v_max_i32_e32 v175, 17, v167
	v_max_i32_e32 v176, 18, v167
	v_max_i32_e32 v177, 19, v167
	v_max_i32_e32 v180, 20, v167
	v_max_i32_e32 v181, 21, v167
	v_max_i32_e32 v182, 22, v167
	v_max_i32_e32 v183, 23, v167
	v_max_i32_e32 v184, 32, v167
	v_max_i32_e32 v185, 33, v167
	v_max_i32_e32 v186, 34, v167
	v_max_i32_e32 v187, 35, v167
	v_max_i32_e32 v188, 36, v167
	v_max_i32_e32 v189, 37, v167
	v_max_i32_e32 v190, 38, v167
	v_max_i32_e32 v191, 39, v167
	v_max_i32_e32 v192, 48, v167
	v_max_i32_e32 v193, 49, v167
	v_max_i32_e32 v194, 50, v167
	v_max_i32_e32 v195, 51, v167
	v_max_i32_e32 v196, 52, v167
	v_max_i32_e32 v197, 53, v167
	v_max_i32_e32 v198, 54, v167
	v_max_i32_e32 v199, 55, v167
	v_add_u32_e32 v15, -1, v15
	v_add_u32_e32 v168, -2, v168
	v_add_u32_e32 v169, -3, v169
	v_add_u32_e32 v170, -4, v170
	v_add_u32_e32 v171, -5, v171
	v_add_u32_e32 v172, -6, v172
	v_add_u32_e32 v173, -7, v173
	v_add_u32_e32 v174, -16, v174
	v_subrev_u32_e32 v175, 17, v175
	v_subrev_u32_e32 v176, 18, v176
	v_subrev_u32_e32 v177, 19, v177
	v_subrev_u32_e32 v180, 20, v180
	v_subrev_u32_e32 v181, 21, v181
	v_subrev_u32_e32 v182, 22, v182
	v_subrev_u32_e32 v183, 23, v183
	v_subrev_u32_e32 v184, 32, v184
	v_subrev_u32_e32 v185, 33, v185
	v_subrev_u32_e32 v186, 34, v186
	v_subrev_u32_e32 v187, 35, v187
	v_subrev_u32_e32 v188, 36, v188
	v_subrev_u32_e32 v189, 37, v189
	v_subrev_u32_e32 v190, 38, v190
	v_subrev_u32_e32 v191, 39, v191
	v_subrev_u32_e32 v192, 48, v192
	v_subrev_u32_e32 v193, 49, v193
	v_subrev_u32_e32 v194, 50, v194
	v_subrev_u32_e32 v195, 51, v195
	v_subrev_u32_e32 v196, 52, v196
	v_subrev_u32_e32 v197, 53, v197
	v_subrev_u32_e32 v198, 54, v198
	v_subrev_u32_e32 v199, 55, v199
	v_med3_i32 v14, v167, 0, v235
	s_add_i32 s41, s76, 0x100
	v_min_u32_e32 v15, 0x80, v15
	v_min_u32_e32 v168, 0x80, v168
	v_min_u32_e32 v169, 0x80, v169
	v_min_u32_e32 v170, 0x80, v170
	v_min_u32_e32 v171, 0x80, v171
	v_min_u32_e32 v172, 0x80, v172
	v_min_u32_e32 v173, 0x80, v173
	v_min_u32_e32 v174, 0x80, v174
	v_min_u32_e32 v175, 0x80, v175
	v_min_u32_e32 v176, 0x80, v176
	v_min_u32_e32 v177, 0x80, v177
	v_min_u32_e32 v180, 0x80, v180
	v_min_u32_e32 v181, 0x80, v181
	v_min_u32_e32 v182, 0x80, v182
	v_min_u32_e32 v183, 0x80, v183
	v_min_u32_e32 v184, 0x80, v184
	v_min_u32_e32 v185, 0x80, v185
	v_min_u32_e32 v186, 0x80, v186
	v_min_u32_e32 v187, 0x80, v187
	v_min_u32_e32 v188, 0x80, v188
	v_min_u32_e32 v189, 0x80, v189
	v_min_u32_e32 v190, 0x80, v190
	v_min_u32_e32 v191, 0x80, v191
	v_min_u32_e32 v192, 0x80, v192
	v_min_u32_e32 v193, 0x80, v193
	v_min_u32_e32 v194, 0x80, v194
	v_min_u32_e32 v195, 0x80, v195
	v_min_u32_e32 v196, 0x80, v196
	v_min_u32_e32 v197, 0x80, v197
	v_min_u32_e32 v198, 0x80, v198
	v_min_u32_e32 v199, 0x80, v199
	v_lshl_add_u32 v14, v14, 2, s41
	v_lshl_add_u32 v15, v15, 2, s41
	v_lshl_add_u32 v168, v168, 2, s41
	v_lshl_add_u32 v169, v169, 2, s41
	v_lshl_add_u32 v170, v170, 2, s41
	v_lshl_add_u32 v171, v171, 2, s41
	v_lshl_add_u32 v172, v172, 2, s41
	v_lshl_add_u32 v173, v173, 2, s41
	v_lshl_add_u32 v174, v174, 2, s41
	v_lshl_add_u32 v175, v175, 2, s41
	v_lshl_add_u32 v176, v176, 2, s41
	v_lshl_add_u32 v177, v177, 2, s41
	v_lshl_add_u32 v180, v180, 2, s41
	v_lshl_add_u32 v181, v181, 2, s41
	v_lshl_add_u32 v182, v182, 2, s41
	v_lshl_add_u32 v183, v183, 2, s41
	v_lshl_add_u32 v184, v184, 2, s41
	v_lshl_add_u32 v185, v185, 2, s41
	v_lshl_add_u32 v186, v186, 2, s41
	v_lshl_add_u32 v187, v187, 2, s41
	v_lshl_add_u32 v188, v188, 2, s41
	v_lshl_add_u32 v189, v189, 2, s41
	v_lshl_add_u32 v190, v190, 2, s41
	v_lshl_add_u32 v191, v191, 2, s41
	v_lshl_add_u32 v192, v192, 2, s41
	v_lshl_add_u32 v193, v193, 2, s41
	v_lshl_add_u32 v194, v194, 2, s41
	v_lshl_add_u32 v195, v195, 2, s41
	v_lshl_add_u32 v196, v196, 2, s41
	v_lshl_add_u32 v197, v197, 2, s41
	v_lshl_add_u32 v198, v198, 2, s41
	v_lshl_add_u32 v199, v199, 2, s41
	ds_read_b32 v14, v14
	ds_read_b32 v15, v15
	ds_read_b32 v168, v168
	ds_read_b32 v169, v169
	ds_read_b32 v170, v170
	ds_read_b32 v171, v171
	ds_read_b32 v172, v172
	ds_read_b32 v173, v173
	ds_read_b32 v174, v174
	ds_read_b32 v175, v175
	ds_read_b32 v176, v176
	ds_read_b32 v177, v177
	ds_read_b32 v180, v180
	ds_read_b32 v181, v181
	ds_read_b32 v182, v182
	ds_read_b32 v183, v183
	ds_read_b32 v184, v184
	ds_read_b32 v185, v185
	ds_read_b32 v186, v186
	ds_read_b32 v187, v187
	ds_read_b32 v188, v188
	ds_read_b32 v189, v189
	ds_read_b32 v190, v190
	ds_read_b32 v191, v191
	ds_read_b32 v192, v192
	ds_read_b32 v193, v193
	ds_read_b32 v194, v194
	ds_read_b32 v195, v195
	ds_read_b32 v196, v196
	ds_read_b32 v197, v197
	ds_read_b32 v198, v198
	ds_read_b32 v199, v199
	s_waitcnt lgkmcnt(0)
	v_pk_add_f32 v[108:109], v[108:109], v[180:181]
	v_pk_add_f32 v[106:107], v[106:107], v[176:177]
	v_pk_add_f32 v[110:111], v[110:111], v[182:183]
	v_pk_add_f32 v[104:105], v[104:105], v[174:175]
	v_pk_add_f32 v[102:103], v[102:103], v[172:173]
	v_pk_add_f32 v[100:101], v[100:101], v[170:171]
	v_pk_add_f32 v[98:99], v[98:99], v[168:169]
	v_pk_add_f32 v[96:97], v[96:97], v[14:15]
	v_pk_add_f32 v[94:95], v[94:95], v[198:199]
	v_pk_add_f32 v[92:93], v[92:93], v[196:197]
	v_pk_add_f32 v[90:91], v[90:91], v[194:195]
	v_pk_add_f32 v[88:89], v[88:89], v[192:193]
	v_pk_add_f32 v[86:87], v[86:87], v[190:191]
	v_pk_add_f32 v[84:85], v[84:85], v[188:189]
	v_pk_add_f32 v[82:83], v[82:83], v[186:187]
	v_pk_add_f32 v[80:81], v[80:81], v[184:185]
